# scan: operands staged through registers (global_load_dwordx4, ds_write_b128 one chunk later) instead of LDS-DMA pieces, whose issue cost sat on each chunk's critical path
# baseline (speedup 1.0000x reference)
.LBB0_362:
	v_readlane_b32 s4, v242, 8
	s_waitcnt lgkmcnt(0)
	s_barrier
	v_mbcnt_lo_u32_b32 v0, -1, 0
	v_mbcnt_hi_u32_b32 v0, -1, v0
	v_mov_b32_e32 v30, 0
	s_mov_b32 s4, s40
	s_mov_b32 s5, s77
	v_and_b32_e32 v1, 15, v0
	v_lshrrev_b32_e32 v2, 4, v0
	s_lshr_b32 s38, s5, 1
	s_and_b32 s39, s5, 1
	s_lshr_b32 s7, s4, 2
	s_lshl_b32 s7, s7, 5
	s_and_b32 s8, s4, 3
	s_lshl_b32 s9, s7, 14
	s_add_u32 s10, s92, 0x9000000
	s_addc_u32 s11, s93, 0
	s_add_u32 s10, s10, s9
	s_addc_u32 s11, s11, 0
	s_add_u32 s12, s92, 0xb000000
	s_addc_u32 s13, s93, 0
	s_add_u32 s12, s12, s9
	s_addc_u32 s13, s13, 0
	s_add_u32 s14, s92, 0xd000000
	s_addc_u32 s15, s93, 0
	s_add_u32 s14, s14, s9
	s_addc_u32 s15, s15, 0
	s_lshl_b32 s26, s7, 13
	s_add_u32 s18, s92, 0xf000000
	s_addc_u32 s19, s93, 0
	s_add_u32 s18, s18, s26
	s_addc_u32 s19, s19, 0
	s_add_u32 s24, s90, 0x2000000
	s_addc_u32 s25, s91, 0
	s_add_u32 s24, s24, s9
	s_addc_u32 s25, s25, 0
	s_lshl_b32 s26, s8, 6
	s_add_u32 s24, s24, s26
	s_addc_u32 s25, s25, 0
	s_add_u32 s42, s92, 0x500000
	s_addc_u32 s43, s93, 0
	v_and_b32_e32 v26, 31, v0
	v_add_u32_e32 v26, s7, v26
	v_lshlrev_b32_e32 v26, 2, v26
	global_load_dword v24, v26, s[42:43]
	v_mov_b32_e32 v30, 0
	s_lshl_b32 s30, s5, 11
	s_lshl_b32 s31, s5, 10
	s_and_b32 s32, s5, 3
	s_lshl_b32 s32, s32, 10
	v_lshlrev_b32_e32 v178, 4, v0
	v_add_u32_e32 v180, s31, v178
	v_add_u32_e32 v181, s32, v178
	v_add_u32_e32 v178, s30, v178
	v_add_u32_e32 v179, 0x10000, v178
	v_add_u32_e32 v180, 0x18000, v180
	v_add_u32_e32 v181, 0x1f400, v181
	s_lshl_b32 s7, s5, 3
	v_add_u32_e32 v26, s7, v2
	v_and_b32_e32 v27, 15, v26
	v_xor_b32_e32 v27, v27, v1
	v_lshlrev_b32_e32 v27, 4, v27
	v_lshl_add_u32 v3, v26, 8, v27
	s_lshl_b32 s7, s5, 3
	s_add_u32 s7, s7, 4
	v_add_u32_e32 v26, s7, v2
	v_and_b32_e32 v27, 15, v26
	v_xor_b32_e32 v27, v27, v1
	v_lshlrev_b32_e32 v27, 4, v27
	v_lshl_add_u32 v4, v26, 8, v27
	v_lshrrev_b32_e32 v28, 3, v0
	v_and_b32_e32 v29, 7, v0
	s_lshl_b32 s7, s5, 4
	v_add_u32_e32 v26, s7, v28
	v_bfe_u32 v27, v26, 1, 3
	v_xor_b32_e32 v27, v27, v29
	v_lshlrev_b32_e32 v27, 4, v27
	v_lshl_add_u32 v5, v26, 7, v27
	s_lshl_b32 s7, s5, 4
	s_add_u32 s7, s7, 8
	v_add_u32_e32 v26, s7, v28
	v_bfe_u32 v27, v26, 1, 3
	v_xor_b32_e32 v27, v27, v29
	v_lshlrev_b32_e32 v27, 4, v27
	v_lshl_add_u32 v6, v26, 7, v27
	s_lshl_b32 s7, s5, 3
	v_add_u32_e32 v26, s7, v28
	v_bfe_u32 v27, v26, 1, 3
	v_xor_b32_e32 v27, v27, v29
	v_lshlrev_b32_e32 v27, 4, v27
	v_lshl_add_u32 v7, v26, 7, v27
	s_and_b32 s7, s5, 3
	s_lshl_b32 s7, s7, 4
	v_lshrrev_b32_e32 v26, 2, v0
	v_add_u32_e32 v26, s7, v26
	v_and_b32_e32 v27, 3, v0
	v_lshlrev_b32_e32 v27, 4, v27
	v_lshl_add_u32 v8, v26, 8, v27
	s_lshl_b32 s7, s39, 4
	v_add_u32_e32 v26, s7, v1
	s_lshl_b32 s8, s38, 4
	v_add_u32_e32 v27, s8, v1
	v_lshlrev_b32_e32 v28, 4, v2
	s_movk_i32 s9, 0x110
	v_mul_lo_u32 v29, v26, s9
	v_add_u32_e32 v10, v29, v28
	v_add_u32_e32 v10, 0x1c000, v10
	v_lshlrev_b32_e32 v31, 3, v2
	s_lshl_b32 s9, s38, 6
	v_add3_u32 v21, v29, v31, s9
	v_add_u32_e32 v21, 0x1c000, v21
	s_movk_i32 s9, 0x90
	v_mul_lo_u32 v29, v26, s9
	v_add_u32_e32 v19, v29, v28
	v_add_u32_e32 v19, 0x1e200, v19
	s_lshl_b32 s9, s38, 5
	v_add3_u32 v20, v29, v31, s9
	v_add_u32_e32 v20, 0x1e200, v20
	v_add_u32_e32 v29, 0, v2
	v_xor_b32_e32 v29, v29, v1
	v_lshlrev_b32_e32 v29, 4, v29
	v_lshl_add_u32 v11, v27, 8, v29
	v_add_u32_e32 v29, 4, v2
	v_xor_b32_e32 v29, v29, v1
	v_lshlrev_b32_e32 v29, 4, v29
	v_lshl_add_u32 v12, v27, 8, v29
	v_add_u32_e32 v29, 8, v2
	v_xor_b32_e32 v29, v29, v1
	v_lshlrev_b32_e32 v29, 4, v29
	v_lshl_add_u32 v13, v27, 8, v29
	v_add_u32_e32 v29, 12, v2
	v_xor_b32_e32 v29, v29, v1
	v_lshlrev_b32_e32 v29, 4, v29
	v_lshl_add_u32 v14, v27, 8, v29
	v_lshrrev_b32_e32 v31, 1, v1
	s_lshl_b32 s9, s38, 5
	v_add_u32_e32 v26, s9, v1
	v_add_u32_e32 v29, 0, v2
	v_xor_b32_e32 v29, v29, v31
	v_lshlrev_b32_e32 v29, 4, v29
	v_lshl_add_u32 v15, v26, 7, v29
	v_add_u32_e32 v15, 0x10000, v15
	v_lshl_add_u32 v17, v27, 7, v29
	v_add_u32_e32 v17, 0x18000, v17
	v_add_u32_e32 v29, 4, v2
	v_xor_b32_e32 v29, v29, v31
	v_lshlrev_b32_e32 v29, 4, v29
	v_lshl_add_u32 v16, v26, 7, v29
	v_add_u32_e32 v16, 0x10000, v16
	v_lshl_add_u32 v18, v27, 7, v29
	v_add_u32_e32 v18, 0x18000, v18
	s_lshl_b32 s9, s38, 10
	v_lshlrev_b32_e32 v29, 8, v2
	v_add_u32_e32 v29, s9, v29
	s_lshl_b32 s9, s39, 5
	v_lshl_add_u32 v29, v1, 1, v29
	v_add_u32_e32 v29, s9, v29
	v_add_u32_e32 v22, 0x1f400, v29
	v_lshlrev_b32_e32 v29, 3, v2
	v_lshl_add_u32 v29, v27, 8, v29
	v_add_u32_e32 v9, s9, v29
	v_mov_b32_e32 v32, 0
	v_mov_b32_e32 v33, 0
	v_mov_b32_e32 v34, 0
	v_mov_b32_e32 v35, 0
	v_lshl_add_u32 v26, s5, 6, v0
	v_lshlrev_b32_e32 v27, 4, v26
	v_add_u32_e32 v27, 0x1c000, v27
	ds_write_b128 v27, v[32:35]
	v_and_b32_e32 v26, 31, v26
	v_lshlrev_b32_e32 v27, 4, v26
	v_add_u32_e32 v27, 0x1e000, v27
	ds_write_b128 v27, v[32:35]
	v_mov_b32_e32 v92, 0
	v_mov_b32_e32 v93, 0
	v_mov_b32_e32 v94, 0
	v_mov_b32_e32 v95, 0
	v_mov_b32_e32 v96, 0
	v_mov_b32_e32 v97, 0
	v_mov_b32_e32 v98, 0
	v_mov_b32_e32 v99, 0
	s_mov_b32 s6, 0
	global_load_dwordx4 v[148:151], v8, s[24:25]
	global_load_dwordx4 v[162:165], v3, s[10:11]
	global_load_dwordx4 v[166:169], v4, s[10:11]
	global_load_dwordx4 v[170:173], v3, s[12:13]
	global_load_dwordx4 v[174:177], v4, s[12:13]
	s_waitcnt vmcnt(0)
	ds_write_b128 v181, v[148:151]
	ds_write_b128 v178, v[162:165] offset:0
	ds_write_b128 v178, v[166:169] offset:1024
	ds_write_b128 v178, v[170:173] offset:32768
	ds_write_b128 v178, v[174:177] offset:33792
	global_load_dwordx4 v[136:139], v5, s[14:15]
	global_load_dwordx4 v[140:143], v6, s[14:15]
	global_load_dwordx4 v[144:147], v7, s[18:19]
	s_add_u32 s26, s24, 0x4000
	s_addc_u32 s27, s25, 0
	global_load_dwordx4 v[148:151], v8, s[26:27]
	s_add_u32 s26, s10, 0x4000
	s_addc_u32 s27, s11, 0
	global_load_dwordx4 v[162:165], v3, s[26:27]
	global_load_dwordx4 v[166:169], v4, s[26:27]
	s_add_u32 s26, s12, 0x4000
	s_addc_u32 s27, s13, 0
	global_load_dwordx4 v[170:173], v3, s[26:27]
	global_load_dwordx4 v[174:177], v4, s[26:27]
	global_load_dword v25, v30, s[42:43]
	s_waitcnt lgkmcnt(0)
	s_barrier
.Lscan_loop:
	s_and_b32 s7, s6, 3
	s_lshl_b32 s7, s7, 12
	v_add_u32_e32 v23, s7, v22
	ds_read_b128 v[32:35], v10 offset:0
	ds_read_b128 v[48:51], v11 offset:0
	ds_read_b128 v[36:39], v10 offset:64
	ds_read_b128 v[52:55], v12 offset:0
	ds_read_b128 v[40:43], v10 offset:128
	ds_read_b128 v[56:59], v13 offset:0
	ds_read_b128 v[44:47], v10 offset:192
	ds_read_b128 v[60:63], v14 offset:0
	ds_read_u16 v80, v23 offset:0
	ds_read_u16 v81, v23 offset:64
	ds_read_u16 v82, v23 offset:128
	ds_read_u16 v83, v23 offset:192
	s_add_u32 s33, s6, 1
	s_min_u32 s33, s33, 31
	s_add_u32 s36, s6, 2
	s_min_u32 s36, s36, 31
	v_readlane_b32 s37, v24, s6
	s_nop 1
	v_mul_f32_e32 v92, s37, v92
	v_mul_f32_e32 v93, s37, v93
	v_mul_f32_e32 v94, s37, v94
	v_mul_f32_e32 v95, s37, v95
	v_mul_f32_e32 v96, s37, v96
	v_mul_f32_e32 v97, s37, v97
	v_mul_f32_e32 v98, s37, v98
	v_mul_f32_e32 v99, s37, v99
	s_waitcnt lgkmcnt(10)
	v_mfma_f32_16x16x32_bf16 v[84:87], v[48:51], v[32:35], 0
	s_waitcnt lgkmcnt(8)
	v_mfma_f32_16x16x32_bf16 v[84:87], v[52:55], v[36:39], v[84:87]
	s_waitcnt lgkmcnt(6)
	v_mfma_f32_16x16x32_bf16 v[84:87], v[56:59], v[40:43], v[84:87]
	s_waitcnt lgkmcnt(4)
	v_mfma_f32_16x16x32_bf16 v[84:87], v[60:63], v[44:47], v[84:87]
	ds_read_b128 v[64:67], v11 offset:32768
	ds_read_b128 v[68:71], v12 offset:32768
	ds_read_b128 v[72:75], v13 offset:32768
	ds_read_b128 v[76:79], v14 offset:32768
	s_waitcnt lgkmcnt(4)
	v_lshlrev_b32_e32 v80, 16, v80
	v_lshlrev_b32_e32 v81, 16, v81
	v_lshlrev_b32_e32 v82, 16, v82
	v_lshlrev_b32_e32 v83, 16, v83
	v_sub_f32_e32 v26, v80, v84
	v_sub_f32_e32 v27, v81, v85
	v_sub_f32_e32 v28, v82, v86
	v_sub_f32_e32 v29, v83, v87
	v_cvt_pk_bf16_f32 v26, v26, v27
	v_cvt_pk_bf16_f32 v27, v28, v29
	ds_write_b64 v20, v[26:27]
	s_waitcnt vmcnt(5)
	ds_write_b128 v179, v[136:139] offset:0
	ds_write_b128 v179, v[140:143] offset:1024
	ds_write_b128 v180, v[144:147] offset:0
	s_add_u32 s8, s6, 1
	s_and_b32 s8, s8, 3
	s_lshl_b32 s8, s8, 12
	v_add_u32_e32 v182, s8, v181
	ds_write_b128 v182, v[148:151]
	s_lshl_b32 s7, s33, 14
	s_add_u32 s26, s14, s7
	s_addc_u32 s27, s15, 0
	global_load_dwordx4 v[136:139], v5, s[26:27]
	global_load_dwordx4 v[140:143], v6, s[26:27]
	s_lshl_b32 s7, s33, 13
	s_add_u32 s28, s18, s7
	s_addc_u32 s29, s19, 0
	global_load_dwordx4 v[144:147], v7, s[28:29]
	s_lshl_b32 s7, s36, 14
	s_add_u32 s26, s24, s7
	s_addc_u32 s27, s25, 0
	global_load_dwordx4 v[148:151], v8, s[26:27]
	s_waitcnt lgkmcnt(0)
	s_barrier
	ds_read_b128 v[100:103], v19
	ds_read_b128 v[108:111], v15 offset:0
	ds_read_b128 v[112:115], v15 offset:2048
	ds_read_b128 v[104:107], v19 offset:64
	ds_read_b128 v[116:119], v16 offset:0
	ds_read_b128 v[120:123], v16 offset:2048
	ds_read_b128 v[124:127], v17 offset:0
	ds_read_b128 v[128:131], v18 offset:0
	v_mfma_f32_16x16x32_bf16 v[88:91], v[32:35], v[64:67], 0
	v_mfma_f32_16x16x32_bf16 v[88:91], v[36:39], v[68:71], v[88:91]
	v_mfma_f32_16x16x32_bf16 v[88:91], v[40:43], v[72:75], v[88:91]
	v_mfma_f32_16x16x32_bf16 v[88:91], v[44:47], v[76:79], v[88:91]
	s_waitcnt lgkmcnt(6)
	v_mfma_f32_16x16x32_bf16 v[92:95], v[108:111], v[100:103], v[92:95]
	s_waitcnt lgkmcnt(5)
	v_mfma_f32_16x16x32_bf16 v[96:99], v[112:115], v[100:103], v[96:99]
	s_waitcnt lgkmcnt(3)
	v_mfma_f32_16x16x32_bf16 v[92:95], v[116:119], v[104:107], v[92:95]
	s_waitcnt lgkmcnt(2)
	v_mfma_f32_16x16x32_bf16 v[96:99], v[120:123], v[104:107], v[96:99]
	s_waitcnt lgkmcnt(1)
	v_mfma_f32_16x16x32_bf16 v[88:91], v[100:103], v[124:127], v[88:91]
	s_waitcnt lgkmcnt(0)
	v_mfma_f32_16x16x32_bf16 v[88:91], v[104:107], v[128:131], v[88:91]
	s_lshl_b32 s7, s6, 14
	s_add_u32 s28, s24, s7
	s_addc_u32 s29, s25, 0
	s_nop 1
	v_cvt_pk_bf16_f32 v26, v92, v93
	v_cvt_pk_bf16_f32 v27, v94, v95
	v_cvt_pk_bf16_f32 v28, v96, v97
	v_cvt_pk_bf16_f32 v29, v98, v99
	ds_write_b64 v21, v[26:27]
	ds_write_b64 v21, v[28:29] offset:32
	s_waitcnt vmcnt(5)
	ds_write_b128 v178, v[162:165] offset:16384
	ds_write_b128 v178, v[166:169] offset:17408
	ds_write_b128 v178, v[170:173] offset:49152
	ds_write_b128 v178, v[174:177] offset:50176
	s_lshl_b32 s7, s36, 14
	s_add_u32 s26, s10, s7
	s_addc_u32 s27, s11, 0
	global_load_dwordx4 v[162:165], v3, s[26:27]
	global_load_dwordx4 v[166:169], v4, s[26:27]
	s_lshl_b32 s7, s36, 14
	s_add_u32 s26, s12, s7
	s_addc_u32 s27, s13, 0
	global_load_dwordx4 v[170:173], v3, s[26:27]
	global_load_dwordx4 v[174:177], v4, s[26:27]
	v_cvt_pk_bf16_f32 v80, v88, v89
	v_cvt_pk_bf16_f32 v81, v90, v91
	global_store_dwordx2 v9, v[80:81], s[28:29]
	s_add_u32 s6, s6, 1
	s_waitcnt lgkmcnt(0)
	s_barrier
	s_and_b32 s7, s6, 3
	s_lshl_b32 s7, s7, 12
	v_add_u32_e32 v23, s7, v22
	ds_read_b128 v[32:35], v10 offset:0
	ds_read_b128 v[48:51], v11 offset:16384
	ds_read_b128 v[36:39], v10 offset:64
	ds_read_b128 v[52:55], v12 offset:16384
	ds_read_b128 v[40:43], v10 offset:128
	ds_read_b128 v[56:59], v13 offset:16384
	ds_read_b128 v[44:47], v10 offset:192
	ds_read_b128 v[60:63], v14 offset:16384
	ds_read_u16 v80, v23 offset:0
	ds_read_u16 v81, v23 offset:64
	ds_read_u16 v82, v23 offset:128
	ds_read_u16 v83, v23 offset:192
	s_add_u32 s33, s6, 1
	s_min_u32 s33, s33, 31
	s_add_u32 s36, s6, 2
	s_min_u32 s36, s36, 31
	v_readlane_b32 s37, v24, s6
	s_nop 1
	v_mul_f32_e32 v92, s37, v92
	v_mul_f32_e32 v93, s37, v93
	v_mul_f32_e32 v94, s37, v94
	v_mul_f32_e32 v95, s37, v95
	v_mul_f32_e32 v96, s37, v96
	v_mul_f32_e32 v97, s37, v97
	v_mul_f32_e32 v98, s37, v98
	v_mul_f32_e32 v99, s37, v99
	s_waitcnt lgkmcnt(10)
	v_mfma_f32_16x16x32_bf16 v[84:87], v[48:51], v[32:35], 0
	s_waitcnt lgkmcnt(8)
	v_mfma_f32_16x16x32_bf16 v[84:87], v[52:55], v[36:39], v[84:87]
	s_waitcnt lgkmcnt(6)
	v_mfma_f32_16x16x32_bf16 v[84:87], v[56:59], v[40:43], v[84:87]
	s_waitcnt lgkmcnt(4)
	v_mfma_f32_16x16x32_bf16 v[84:87], v[60:63], v[44:47], v[84:87]
	ds_read_b128 v[64:67], v11 offset:49152
	ds_read_b128 v[68:71], v12 offset:49152
	ds_read_b128 v[72:75], v13 offset:49152
	ds_read_b128 v[76:79], v14 offset:49152
	s_waitcnt lgkmcnt(4)
	v_lshlrev_b32_e32 v80, 16, v80
	v_lshlrev_b32_e32 v81, 16, v81
	v_lshlrev_b32_e32 v82, 16, v82
	v_lshlrev_b32_e32 v83, 16, v83
	v_sub_f32_e32 v26, v80, v84
	v_sub_f32_e32 v27, v81, v85
	v_sub_f32_e32 v28, v82, v86
	v_sub_f32_e32 v29, v83, v87
	v_cvt_pk_bf16_f32 v26, v26, v27
	v_cvt_pk_bf16_f32 v27, v28, v29
	ds_write_b64 v20, v[26:27]
	s_waitcnt vmcnt(5)
	ds_write_b128 v179, v[136:139] offset:16384
	ds_write_b128 v179, v[140:143] offset:17408
	ds_write_b128 v180, v[144:147] offset:8192
	s_add_u32 s8, s6, 1
	s_and_b32 s8, s8, 3
	s_lshl_b32 s8, s8, 12
	v_add_u32_e32 v182, s8, v181
	ds_write_b128 v182, v[148:151]
	s_lshl_b32 s7, s33, 14
	s_add_u32 s26, s14, s7
	s_addc_u32 s27, s15, 0
	global_load_dwordx4 v[136:139], v5, s[26:27]
	global_load_dwordx4 v[140:143], v6, s[26:27]
	s_lshl_b32 s7, s33, 13
	s_add_u32 s28, s18, s7
	s_addc_u32 s29, s19, 0
	global_load_dwordx4 v[144:147], v7, s[28:29]
	s_lshl_b32 s7, s36, 14
	s_add_u32 s26, s24, s7
	s_addc_u32 s27, s25, 0
	global_load_dwordx4 v[148:151], v8, s[26:27]
	s_waitcnt lgkmcnt(0)
	s_barrier
	ds_read_b128 v[100:103], v19
	ds_read_b128 v[108:111], v15 offset:16384
	ds_read_b128 v[112:115], v15 offset:18432
	ds_read_b128 v[104:107], v19 offset:64
	ds_read_b128 v[116:119], v16 offset:16384
	ds_read_b128 v[120:123], v16 offset:18432
	ds_read_b128 v[124:127], v17 offset:8192
	ds_read_b128 v[128:131], v18 offset:8192
	v_mfma_f32_16x16x32_bf16 v[88:91], v[32:35], v[64:67], 0
	v_mfma_f32_16x16x32_bf16 v[88:91], v[36:39], v[68:71], v[88:91]
	v_mfma_f32_16x16x32_bf16 v[88:91], v[40:43], v[72:75], v[88:91]
	v_mfma_f32_16x16x32_bf16 v[88:91], v[44:47], v[76:79], v[88:91]
	s_waitcnt lgkmcnt(6)
	v_mfma_f32_16x16x32_bf16 v[92:95], v[108:111], v[100:103], v[92:95]
	s_waitcnt lgkmcnt(5)
	v_mfma_f32_16x16x32_bf16 v[96:99], v[112:115], v[100:103], v[96:99]
	s_waitcnt lgkmcnt(3)
	v_mfma_f32_16x16x32_bf16 v[92:95], v[116:119], v[104:107], v[92:95]
	s_waitcnt lgkmcnt(2)
	v_mfma_f32_16x16x32_bf16 v[96:99], v[120:123], v[104:107], v[96:99]
	s_waitcnt lgkmcnt(1)
	v_mfma_f32_16x16x32_bf16 v[88:91], v[100:103], v[124:127], v[88:91]
	s_waitcnt lgkmcnt(0)
	v_mfma_f32_16x16x32_bf16 v[88:91], v[104:107], v[128:131], v[88:91]
	s_lshl_b32 s7, s6, 14
	s_add_u32 s28, s24, s7
	s_addc_u32 s29, s25, 0
	s_nop 1
	v_cvt_pk_bf16_f32 v26, v92, v93
	v_cvt_pk_bf16_f32 v27, v94, v95
	v_cvt_pk_bf16_f32 v28, v96, v97
	v_cvt_pk_bf16_f32 v29, v98, v99
	ds_write_b64 v21, v[26:27]
	ds_write_b64 v21, v[28:29] offset:32
	s_waitcnt vmcnt(5)
	ds_write_b128 v178, v[162:165] offset:0
	ds_write_b128 v178, v[166:169] offset:1024
	ds_write_b128 v178, v[170:173] offset:32768
	ds_write_b128 v178, v[174:177] offset:33792
	s_lshl_b32 s7, s36, 14
	s_add_u32 s26, s10, s7
	s_addc_u32 s27, s11, 0
	global_load_dwordx4 v[162:165], v3, s[26:27]
	global_load_dwordx4 v[166:169], v4, s[26:27]
	s_lshl_b32 s7, s36, 14
	s_add_u32 s26, s12, s7
	s_addc_u32 s27, s13, 0
	global_load_dwordx4 v[170:173], v3, s[26:27]
	global_load_dwordx4 v[174:177], v4, s[26:27]
	v_cvt_pk_bf16_f32 v80, v88, v89
	v_cvt_pk_bf16_f32 v81, v90, v91
	global_store_dwordx2 v9, v[80:81], s[28:29]
	s_add_u32 s6, s6, 1
	s_waitcnt lgkmcnt(0)
	s_barrier
	s_cmp_lt_u32 s6, 32
	s_cbranch_scc1 .Lscan_loop
	s_lshl_b32 s56, s77, 5
	s_and_b32 s57, s40, 3
	s_lshl_b32 s72, s40, 5
	s_waitcnt vmcnt(0)
	v_readfirstlane_b32 s3, v194
	s_cmp_gt_u32 s3, 63
	s_barrier
	s_cbranch_scc1 .LBB0_421
	s_waitcnt vmcnt(2)
	v_mbcnt_lo_u32_b32 v0, -1, 0
	v_mbcnt_hi_u32_b32 v0, -1, v0
	s_nop 0
	v_cmp_eq_u32_e32 vcc, 0, v0
	s_and_saveexec_b64 s[6:7], vcc
	s_cbranch_execz .LBB0_420
	s_add_i32 s3, 0, 0x23ff0
	v_mov_b32_e32 v0, s3
	s_waitcnt vmcnt(0) expcnt(0) lgkmcnt(0)
	ds_read_b32 v2, v0
	s_add_i32 s3, 0, 0x23ff4
	v_mov_b32_e32 v0, s3
	ds_read_b32 v0, v0
	s_waitcnt lgkmcnt(1)
	v_cmp_ne_u32_e32 vcc, 0, v2
	s_cbranch_vccnz .LBB0_384
	s_mov_b32 s3, 1
	v_mov_b32_e32 v16, 0
	s_branch .LBB0_372
